# code placement: 60 bytes of padding in the in-projection set-up so that the in-projection K-loop (60% of the time) sits at the baseline's byte phase again (was shifted +68 B, i.e. 4 mod 8, by the earl
# speedup vs baseline: 1.0067x; 1.0067x over previous
.LBB0_240:
	s_nop 0
	s_nop 0
	s_nop 0
	s_nop 0
	s_nop 0
	s_nop 0
	s_nop 0
	s_nop 0
	s_nop 0
	s_nop 0
	s_nop 0
	s_nop 0
	s_nop 0
	s_nop 0
	s_nop 0
	s_lshl_b32 s8, s94, 7
	s_ashr_i32 s9, s8, 31
	v_bfe_u32 v15, v200, 4, 2
	s_lshl_b64 s[8:9], s[8:9], 2
	v_readlane_b32 s3, v252, 27
	v_and_b32_e32 v14, 15, v200
	v_lshlrev_b32_e32 v17, 4, v15
	v_readlane_b32 s14, v253, 2
	s_add_u32 s84, s3, s8
	v_readlane_b32 s3, v252, 28
	v_lshl_or_b32 v166, s1, 6, v14
	v_lshl_or_b32 v14, v14, 6, v17
	v_lshlrev_b32_e32 v17, 2, v200
	v_mov_b32_e32 v135, v193
	v_readlane_b32 s15, v253, 3
	s_addc_u32 s85, s3, s9
	s_and_b32 s50, s2, 3
	s_lshl_b32 s1, s1, 13
	v_and_b32_e32 v17, 32, v17
	s_add_i32 m0, s26, 0x18000
	v_lshl_add_u64 v[0:1], v[0:1], 0, s[42:43]
	v_lshl_add_u64 v[10:11], s[14:15], 0, v[134:135]
	v_mov_b32_e32 v131, v193
	v_bitop3_b32 v18, v14, s1, v17 bitop3:0xde
	s_lshl_b32 s1, s50, 12
	s_waitcnt vmcnt(2)
	s_barrier
	global_load_lds_dwordx4 v[0:1], off
	v_lshl_add_u64 v[0:1], v[2:3], 0, s[42:43]
	s_add_i32 m0, s26, 0x1a000
	s_add_i32 s56, s26, 0x8000
	s_add_i32 s68, s26, 0xa000
	v_lshl_add_u64 v[12:13], s[14:15], 0, v[130:131]
	global_load_lds_dwordx4 v[0:1], off
	v_lshl_add_u64 v[0:1], v[10:11], 0, s[42:43]
	s_mov_b32 m0, s56
	s_add_u32 s2, s6, 0x80080
	global_load_lds_dwordx4 v[0:1], off
	v_lshl_add_u64 v[0:1], v[12:13], 0, s[42:43]
	s_mov_b32 m0, s68
	s_addc_u32 s3, s7, 0
	global_load_lds_dwordx4 v[0:1], off
	s_add_i32 m0, s26, 0x1c000
	v_lshl_add_u64 v[0:1], s[2:3], 0, v[132:133]
	global_load_lds_dwordx4 v[0:1], off
	v_lshl_add_u64 v[0:1], s[2:3], 0, v[128:129]
	s_add_i32 m0, s26, 0x1e000
	v_bitop3_b32 v167, s1, v14, v17 bitop3:0xf6
	global_load_lds_dwordx4 v[0:1], off
	v_lshlrev_b32_e32 v0, 15, v8
	v_and_b32_e32 v0, 0xffff0000, v0
	v_lshl_add_u32 v0, v7, 12, v0
	v_and_b32_e32 v1, 1, v8
	v_lshl_or_b32 v0, v1, 6, v0
	v_lshl_add_u32 v136, v9, 1, v0
	v_lshlrev_b32_e32 v0, 15, v4
	v_and_b32_e32 v0, 0xffff0000, v0
	s_waitcnt vmcnt(6)
	s_cmpk_lt_u32 s0, 0x100
	v_lshl_add_u32 v0, v5, 12, v0
	v_and_b32_e32 v1, 1, v4
	v_readlane_b32 s0, v252, 62
	v_lshlrev_b32_e32 v16, 3, v15
	v_lshl_or_b32 v0, v1, 6, v0
	v_readlane_b32 s1, v252, 63
	v_lshl_or_b32 v168, s50, 5, v16
	s_cselect_b64 s[8:9], -1, 0
	s_mov_b32 s72, 0
	v_cmp_eq_u32_e64 s[2:3], 0, v15
	v_mov_b32_e32 v137, v193
	v_lshl_add_u32 v138, v6, 1, v0
	v_mov_b32_e32 v139, v193
	v_add_u32_e32 v169, 0, v18
	v_readlane_b32 s18, v252, 53
	s_mov_b32 s19, s0
	s_mov_b64 s[0:1], s[14:15]
	s_barrier
	s_branch .LBB0_243
